# attention QK: the two key-half accumulate chains run one after the other; chain 0's row-max tree sits in the shadow of chain 1's MFMAs (no s_nop padding left in diff)
# speedup vs baseline: 1.0132x; 1.0031x over previous
.Latt_diff_p0:
.LBB0_107:
.LBB0_116:
	ds_read_b128 v[112:115], v242 offset:0
	ds_read_b128 v[116:119], v242 offset:32
	ds_read_b128 v[120:123], v242 offset:64
	ds_read_b128 v[124:127], v242 offset:96
	s_add_i32 s30, s52, 2
	s_cmp_ge_u32 s30, s21
	s_cselect_b64 s[46:47], -1, 0
	s_cbranch_scc1 .Latt_diff_dmaend
	s_cmp_lt_u32 s52, 2
	s_cselect_b32 s48, s45, s43
	s_mul_i32 s55, s50, 0x2400
	s_add_i32 s56, s55, s41
	s_mov_b32 m0, s56
	v_lshl_add_u32 v244, s48, 12, v153
	global_load_lds_dwordx4 v244, s[18:19]
	s_ashr_i32 s49, s48, 31
	s_lshl_b64 s[30:31], s[48:49], 1
	s_add_i32 s55, s55, s56
	s_add_i32 m0, s55, 0x6c00
	s_add_u32 s30, s39, s30
	s_addc_u32 s31, s42, s31
	global_load_lds_dwordx4 v150, s[30:31]
	s_add_i32 m0, s55, 0x8c00
	s_and_b64 vcc, exec, s[14:15]
	global_load_lds_dwordx4 v148, s[30:31]
	s_cbranch_vccz .Latt_diff_dmax
.Latt_diff_dmaend:
	s_waitcnt lgkmcnt(3)
	v_mfma_f32_32x32x16_bf16 v[64:79], v[112:115], v[130:133], v[96:111]
	ds_read_b128 v[112:115], v242 offset:4608
	s_waitcnt lgkmcnt(3)
	v_mfma_f32_32x32x16_bf16 v[64:79], v[116:119], v[134:137], v[64:79]
	ds_read_b128 v[116:119], v242 offset:4640
	s_waitcnt lgkmcnt(3)
	v_mfma_f32_32x32x16_bf16 v[64:79], v[120:123], v[138:141], v[64:79]
	ds_read_b128 v[120:123], v242 offset:4672
	s_waitcnt lgkmcnt(3)
	v_mfma_f32_32x32x16_bf16 v[64:79], v[124:127], v[142:145], v[64:79]
	ds_read_b128 v[124:127], v242 offset:4704
	s_waitcnt lgkmcnt(3)
	v_mfma_f32_32x32x16_bf16 v[80:95], v[112:115], v[130:133], v[96:111]
	s_waitcnt lgkmcnt(2)
	v_mfma_f32_32x32x16_bf16 v[80:95], v[116:119], v[134:137], v[80:95]
	s_waitcnt lgkmcnt(1)
	v_mfma_f32_32x32x16_bf16 v[80:95], v[120:123], v[138:141], v[80:95]
	s_waitcnt lgkmcnt(0)
	v_mfma_f32_32x32x16_bf16 v[80:95], v[124:127], v[142:145], v[80:95]
	ds_read_b128 v[112:115], v243 offset:27648
	ds_read_b128 v[116:119], v243 offset:32256
	ds_read_b128 v[120:123], v243 offset:36864
	ds_read_b128 v[124:127], v243 offset:41472
	s_cmp_eq_u32 s52, 0
	s_cselect_b32 s31, 0xff7fffff, 0
	v_max3_f32 v227, v64, v65, v66
	v_max3_f32 v228, v67, v68, v69
	v_max3_f32 v227, v227, v70, v71
	v_max3_f32 v228, v228, v72, v73
	v_max3_f32 v227, v227, v74, v75
	v_max3_f32 v228, v228, v76, v77
	v_max3_f32 v227, v227, v78, v79
	v_max3_f32 v229, v80, v81, v82
	v_max3_f32 v226, v83, v84, v85
	v_max3_f32 v229, v229, v86, v87
	v_max3_f32 v226, v226, v88, v89
	v_max3_f32 v229, v229, v90, v91
	v_max3_f32 v226, v226, v92, v93
	v_max3_f32 v229, v229, v94, v95
	v_max3_f32 v226, v226, v227, v228
	v_max_f32_e32 v226, v226, v229
	v_cmp_lt_f32_e32 vcc, s58, v226
	s_cmp_eq_u32 s52, 0
	s_cbranch_scc1 .Latt_diff_rare
	s_cbranch_vccnz .Latt_diff_rare

.Latt_mla_p0:
.LBB0_178:
.LBB0_191:
	ds_read_b128 v[112:115], v209 offset:0
	ds_read_b128 v[116:119], v209 offset:32
	ds_read_b128 v[120:123], v209 offset:64
	ds_read_b128 v[124:127], v209 offset:96
	ds_read_b128 v[250:253], v209 offset:128
	s_add_i32 s30, s55, 2
	s_cmp_ge_u32 s30, s20
	s_cselect_b64 s[60:61], -1, 0
	s_cbranch_scc1 .Latt_mla_dmaend
	s_cmp_lt_u32 s55, 2
	s_cselect_b32 s62, s51, s49
	s_mul_i32 s57, s52, 0x6400
	s_add_i32 s57, s57, s42
	s_mov_b32 m0, s57
	v_mad_u32_u24 v217, s62, v237, v222
	global_load_lds_dwordx4 v217, s[2:3]
	s_add_i32 m0, s57, 0x2000
	v_mad_u32_u24 v217, s62, v239, v224
	global_load_lds_dwordx4 v217, s[2:3]
	s_add_i32 m0, s57, 0x4000
	v_mad_u32_u24 v217, s62, v241, v226
	global_load_lds_dwordx4 v217, s[2:3]
	s_ashr_i32 s63, s62, 31
	s_lshl_b64 s[30:31], s[62:63], 1
	s_mul_i32 s63, s52, 0x4800
	s_add_i32 s63, s63, s42
	s_add_i32 m0, s63, 0x12c00
	s_add_u32 s30, s21, s30
	s_addc_u32 s31, s43, s31
	global_load_lds_dwordx4 v202, s[30:31]
	s_add_i32 m0, s63, 0x14c00
	s_and_b64 vcc, exec, s[18:19]
	global_load_lds_dwordx4 v200, s[30:31]
	s_cbranch_vccz .Latt_mla_dmax
.Latt_mla_dmaend:
	s_waitcnt lgkmcnt(4)
	v_mfma_f32_32x32x16_bf16 v[64:79], v[112:115], v[130:133], v[96:111]
	ds_read_b128 v[112:115], v209 offset:160
	s_waitcnt lgkmcnt(4)
	v_mfma_f32_32x32x16_bf16 v[64:79], v[116:119], v[134:137], v[64:79]
	ds_read_b128 v[116:119], v209 offset:192
	s_waitcnt lgkmcnt(4)
	v_mfma_f32_32x32x16_bf16 v[64:79], v[120:123], v[138:141], v[64:79]
	ds_read_b128 v[120:123], v209 offset:224
	s_waitcnt lgkmcnt(4)
	v_mfma_f32_32x32x16_bf16 v[64:79], v[124:127], v[142:145], v[64:79]
	ds_read_b128 v[124:127], v209 offset:256
	s_waitcnt lgkmcnt(4)
	v_mfma_f32_32x32x16_bf16 v[64:79], v[250:253], v[146:149], v[64:79]
	ds_read_b128 v[250:253], v209 offset:288
	s_waitcnt lgkmcnt(4)
	v_mfma_f32_32x32x16_bf16 v[64:79], v[112:115], v[150:153], v[64:79]
	ds_read_b128 v[112:115], v209 offset:320
	s_waitcnt lgkmcnt(4)
	v_mfma_f32_32x32x16_bf16 v[64:79], v[116:119], v[154:157], v[64:79]
	ds_read_b128 v[116:119], v209 offset:352
	s_waitcnt lgkmcnt(4)
	v_mfma_f32_32x32x16_bf16 v[64:79], v[120:123], v[158:161], v[64:79]
	ds_read_b128 v[120:123], v209 offset:12800
	s_waitcnt lgkmcnt(4)
	v_mfma_f32_32x32x16_bf16 v[64:79], v[124:127], v[162:165], v[64:79]
	ds_read_b128 v[124:127], v209 offset:12832
	s_waitcnt lgkmcnt(4)
	v_mfma_f32_32x32x16_bf16 v[64:79], v[250:253], v[166:169], v[64:79]
	ds_read_b128 v[250:253], v209 offset:12864
	s_waitcnt lgkmcnt(4)
	v_mfma_f32_32x32x16_bf16 v[64:79], v[112:115], v[170:173], v[64:79]
	ds_read_b128 v[112:115], v209 offset:12896
	s_waitcnt lgkmcnt(4)
	v_mfma_f32_32x32x16_bf16 v[64:79], v[116:119], v[174:177], v[64:79]
	ds_read_b128 v[116:119], v209 offset:12928
	s_waitcnt lgkmcnt(4)
	v_mfma_f32_32x32x16_bf16 v[80:95], v[120:123], v[130:133], v[96:111]
	ds_read_b128 v[120:123], v209 offset:12960
	s_waitcnt lgkmcnt(4)
	v_mfma_f32_32x32x16_bf16 v[80:95], v[124:127], v[134:137], v[80:95]
	ds_read_b128 v[124:127], v209 offset:12992
	s_waitcnt lgkmcnt(4)
	v_mfma_f32_32x32x16_bf16 v[80:95], v[250:253], v[138:141], v[80:95]
	ds_read_b128 v[250:253], v209 offset:13024
	s_waitcnt lgkmcnt(4)
	v_mfma_f32_32x32x16_bf16 v[80:95], v[112:115], v[142:145], v[80:95]
	ds_read_b128 v[112:115], v209 offset:13056
	v_max3_f32 v211, v64, v65, v66
	s_waitcnt lgkmcnt(4)
	v_mfma_f32_32x32x16_bf16 v[80:95], v[116:119], v[146:149], v[80:95]
	ds_read_b128 v[116:119], v209 offset:13088
	v_max3_f32 v213, v67, v68, v69
	s_waitcnt lgkmcnt(4)
	v_mfma_f32_32x32x16_bf16 v[80:95], v[120:123], v[150:153], v[80:95]
	ds_read_b128 v[120:123], v209 offset:13120
	v_max3_f32 v211, v211, v70, v71
	s_waitcnt lgkmcnt(4)
	v_mfma_f32_32x32x16_bf16 v[80:95], v[124:127], v[154:157], v[80:95]
	ds_read_b128 v[124:127], v209 offset:13152
	v_max3_f32 v213, v213, v72, v73
	s_waitcnt lgkmcnt(4)
	v_mfma_f32_32x32x16_bf16 v[80:95], v[250:253], v[158:161], v[80:95]
	v_max3_f32 v211, v211, v74, v75
	s_waitcnt lgkmcnt(3)
	v_mfma_f32_32x32x16_bf16 v[80:95], v[112:115], v[162:165], v[80:95]
	v_max3_f32 v213, v213, v76, v77
	s_waitcnt lgkmcnt(2)
	v_mfma_f32_32x32x16_bf16 v[80:95], v[116:119], v[166:169], v[80:95]
	v_max3_f32 v211, v211, v78, v79
	s_waitcnt lgkmcnt(1)
	v_mfma_f32_32x32x16_bf16 v[80:95], v[120:123], v[170:173], v[80:95]
	s_waitcnt lgkmcnt(0)
	v_mfma_f32_32x32x16_bf16 v[80:95], v[124:127], v[174:177], v[80:95]
	ds_read_b128 v[112:115], v219 offset:0
	ds_read_b128 v[116:119], v219 offset:4608
	ds_read_b128 v[120:123], v219 offset:9216
	s_cmp_eq_u32 s55, 0
	s_cselect_b32 s31, 0xff7fffff, 0
	s_nop 6
	v_max3_f32 v215, v80, v81, v82
	v_max3_f32 v209, v83, v84, v85
	v_max3_f32 v215, v215, v86, v87
	v_max3_f32 v209, v209, v88, v89
	v_max3_f32 v215, v215, v90, v91
	v_max3_f32 v209, v209, v92, v93
	v_max3_f32 v215, v215, v94, v95
	v_max3_f32 v209, v209, v211, v213
	v_max_f32_e32 v209, v209, v215
	v_cmp_lt_f32_e32 vcc, s58, v209
	s_cmp_eq_u32 s55, 0
	s_cbranch_scc1 .Latt_mla_rare
	s_cbranch_vccnz .Latt_mla_rare
